# SSD: M-section masked pair skip; next-step row setup hoisted before the closing barrier; state write moved mid-step
# speedup vs baseline: 1.0315x; 1.0029x over previous
; __device__ __forceinline__ void phase_C1(const Args& a, unsigned char* ws, const int bid, int l, LAS unsigned char* lds, int tid, int wave, int lane) {
;     ...
;         SSD_ISSUE(0);
; #pragma unroll 1
;         for (int step = 0; step < 66; ++step) {
;             const int row0 = SSD_GC(step) * 128;
.Lssd_after_y:
	s_not_b32 s74, s72
	s_add_i32 s4, s4, -1
	s_add_i32 s72, s72, 1
	s_cmp_gt_u32 s72, 1
	s_mov_b64 s[90:91], -1
	s_cselect_b64 s[0:1], -1, 0
	s_and_b64 vcc, exec, s[70:71]
	s_cbranch_vccz .Lssd_t103
	s_and_b64 vcc, exec, s[0:1]
	s_cbranch_vccz .Lssd_t100
	v_readlane_b32 s73, v255, 55
	s_add_i32 s73, s73, s74
	s_mov_b64 s[90:91], 0

; #define LAS __attribute__((address_space(3)))
; __device__ __forceinline__ unsigned cvt_pk_bf16(float lo, float hi) { unsigned r; asm volatile("v_cvt_pk_bf16_f32 %0, %1, %2" : "=v"(r) : "v"(lo), "v"(hi)); return r; }
; #define LDS_BARRIER() do { asm volatile("s_waitcnt lgkmcnt(0)" ::: "memory"); __builtin_amdgcn_s_barrier(); asm volatile("" ::: "memory"); } while (0)
; __device__ __forceinline__ void phase_C1(const Args& a, unsigned char* ws, const int bid, int l, LAS unsigned char* lds, int tid, int wave, int lane) {
;     ...
;             LDS_BARRIER();
; #pragma unroll
;             for (int j = 0; j < 4; ++j) { u32x2 o; o.x = cvt_pk_bf16(Hacc[j][0], Hacc[j][1]); o.y = cvt_pk_bf16(Hacc[j][2], Hacc[j][3]);
;                 *(LAS u32x2*)(L_H + (wr * 16 + fr) * 272 + ((4 * wc + j) * 16 + fq * 4) * 2) = o; }
;         }
.Lssd_t108:
	s_waitcnt lgkmcnt(0)
	s_barrier
	s_cmp_eq_u32 s4, 6
	s_cbranch_scc1 .LBB0_87
	s_branch .LBB0_108

; #define LAS __attribute__((address_space(3)))
; __device__ __forceinline__ void phase_C1(const Args& a, unsigned char* ws, const int bid, int l, LAS unsigned char* lds, int tid, int wave, int lane) {
;     ...
;               for (int kt = 0; kt < 8; ++kt) { const int k0 = kt * 16 + fq * 4;
;                   const bool kept = dir == 0 ? (kt < qt) : (kt > qt);
;                   const float f1 = __expf(csq - refarr[kt]); const f32x4 f2 = *(const LAS f32x4*)(f2dt + k0);
.Lssd_A_ret_main:
	v_mov_b32_e32 v116, 0x22e00
	ds_read_b128 v[244:247], v116
	ds_read_b128 v[248:251], v116 offset:16
	s_or_b64 vcc, s[48:49], s[50:51]
	s_or_b64 vcc, vcc, s[12:13]
	s_or_b64 vcc, vcc, s[14:15]
	s_cbranch_vccz .Lssd_ha_2
	ds_read_b128 v[220:223], v134
	ds_read_b128 v[224:227], v135
.Lssd_ha_2:
	s_or_b64 vcc, s[52:53], s[54:55]
	s_or_b64 vcc, vcc, s[16:17]
	s_or_b64 vcc, vcc, s[18:19]
	s_cbranch_vccz .Lssd_ha_3
	ds_read_b128 v[228:231], v136
	ds_read_b128 v[232:235], v137
.Lssd_ha_3:
	s_or_b64 vcc, s[56:57], s[58:59]
	s_or_b64 vcc, vcc, s[20:21]
	s_or_b64 vcc, vcc, s[22:23]
	s_cbranch_vccz .Lssd_ha_0
	ds_read_b128 v[236:239], v138
	ds_read_b128 v[240:243], v139
.Lssd_ha_0:
	s_orn2_b64 vcc, s[46:47], s[70:71]
	s_or_b64 vcc, vcc, s[10:11]
	s_cbranch_vccz .Lssd_ha_e
	ds_read_b128 v[216:219], v133
	ds_read_b128 v[212:215], v132

; #define LAS __attribute__((address_space(3)))
; __device__ __forceinline__ unsigned cvt_pk_bf16(float lo, float hi) { unsigned r; asm volatile("v_cvt_pk_bf16_f32 %0, %1, %2" : "=v"(r) : "v"(lo), "v"(hi)); return r; }
; __device__ __forceinline__ void phase_C1(const Args& a, unsigned char* ws, const int bid, int l, LAS unsigned char* lds, int tid, int wave, int lane) {
;     ...
;               for (int kt = 0; kt < 8; ++kt) { const int k0 = kt * 16 + fq * 4;
;                   const bool kept = dir == 0 ? (kt < qt) : (kt > qt);
;                   const float f1 = __expf(csq - refarr[kt]); const f32x4 f2 = *(const LAS f32x4*)(f2dt + k0);
;                   float m[4];
; #pragma unroll
;                   for (int r = 0; r < 4; ++r) m[r] = kept ? accA[kt][r] * f1 * f2[r] : 0.f;
;                   u32x2 o; o.x = cvt_pk_bf16(m[0], m[1]); o.y = cvt_pk_bf16(m[2], m[3]);
;                   *(LAS u32x2*)(L_M + q * 272 + k0 * 2) = o; }
;     ...
;             for (int j = 0; j < 4; ++j) { u32x2 o; o.x = cvt_pk_bf16(Hacc[j][0], Hacc[j][1]); o.y = cvt_pk_bf16(Hacc[j][2], Hacc[j][3]);
;                 *(LAS u32x2*)(L_H + (wr * 16 + fr) * 272 + ((4 * wc + j) * 16 + fq * 4) * 2) = o; }
.Lssd_m_section:
	ds_read_b32 v117, v127
	ds_read_b32 v116, v128
	ds_read_b128 v[180:183], v130
	ds_read_b128 v[184:187], v131
	s_waitcnt lgkmcnt(0)
	s_barrier
	s_cmp_eq_u32 s4, 7
	s_cbranch_scc1 .Lssd_nofill
	s_waitcnt vmcnt(9)
	ds_write_b128 v144, v[4:7] offset:34816
	s_waitcnt vmcnt(8)
	ds_write_b128 v144, v[12:15] offset:43520
	s_waitcnt vmcnt(7)
	ds_write_b128 v144, v[20:23] offset:52224
	s_waitcnt vmcnt(6)
	ds_write_b128 v144, v[28:31] offset:60928
	v_cvt_pk_bf16_f32 v188, v40, v41
	v_cvt_pk_bf16_f32 v189, v42, v43
	ds_write_b64 v158, v[188:189]
	v_cvt_pk_bf16_f32 v188, v44, v45
	v_cvt_pk_bf16_f32 v189, v46, v47
	ds_write_b64 v158, v[188:189] offset:32
	v_cvt_pk_bf16_f32 v188, v48, v49
	v_cvt_pk_bf16_f32 v189, v50, v51
	ds_write_b64 v158, v[188:189] offset:64
	v_cvt_pk_bf16_f32 v188, v52, v53
	v_cvt_pk_bf16_f32 v189, v54, v55
	ds_write_b64 v158, v[188:189] offset:96
.Lssd_nofill:
	v_cndmask_b32_e64 v169, v102, v98, s[10:11]
	v_cndmask_b32_e64 v170, v101, v97, s[10:11]
	v_cndmask_b32_e64 v171, v100, v96, s[10:11]
	v_cndmask_b32_e64 v168, v103, v99, s[10:11]
	s_orn2_b64 vcc, s[46:47], s[70:71]
	s_or_b64 vcc, vcc, s[10:11]
	s_cbranch_vccz .Lssd_m_p1
	v_sub_f32_e32 v172, v117, v244
	v_mul_f32_e32 v172, 0x3fb8aa3b, v172
	v_exp_f32_e32 v176, v172
	s_nop 0
	v_readlane_b32 s0, v253, 52
	v_mul_f32_e32 v100, v100, v176
	v_mul_f32_e32 v101, v101, v176
	v_mul_f32_e32 v102, v102, v176
	v_mul_f32_e32 v100, v212, v100
	v_mul_f32_e32 v101, v213, v101
	v_mul_f32_e32 v102, v214, v102
	v_mul_f32_e32 v103, v103, v176
	v_cndmask_b32_e64 v100, 0, v100, s[44:45]
	v_cndmask_b32_e64 v101, 0, v101, s[44:45]
	v_cndmask_b32_e64 v102, 0, v102, s[44:45]
	v_mul_f32_e32 v103, v215, v103
	v_cndmask_b32_e64 v103, 0, v103, s[44:45]
	v_cvt_pk_bf16_f32 v100, v100, v101
	v_cvt_pk_bf16_f32 v101, v102, v103
	v_add_u32_e32 v102, v129, v108
	ds_write_b64 v102, v[100:101]
	v_readlane_b32 s0, v253, 53
	v_sub_f32_e32 v100, v117, v245
	v_mul_f32_e32 v100, 0x3fb8aa3b, v100
	v_exp_f32_e32 v172, v100
	s_nop 0
	v_mul_f32_e32 v96, v96, v172
	v_mul_f32_e32 v97, v97, v172
	v_mul_f32_e32 v96, v216, v96
	v_cndmask_b32_e64 v96, 0, v96, s[46:47]
	v_mul_f32_e32 v97, v217, v97
	v_mul_f32_e32 v98, v98, v172
	v_mul_f32_e32 v99, v99, v172
	v_cndmask_b32_e64 v97, 0, v97, s[46:47]
	v_mul_f32_e32 v98, v218, v98
	v_mul_f32_e32 v99, v219, v99
	v_cvt_pk_bf16_f32 v96, v96, v97
	v_cndmask_b32_e64 v98, 0, v98, s[46:47]
	v_cndmask_b32_e64 v99, 0, v99, s[46:47]
	v_cvt_pk_bf16_f32 v97, v98, v99
	ds_write_b64 v148, v[96:97]
.Lssd_m_p1:
	v_mov_b32_e32 v172, 0
	s_or_b64 vcc, s[48:49], s[50:51]
	s_or_b64 vcc, vcc, s[12:13]
	s_or_b64 vcc, vcc, s[14:15]
	s_cbranch_vccz .Lssd_m_p2
	v_sub_f32_e32 v96, v117, v246
	v_mul_f32_e32 v96, 0x3fb8aa3b, v96
	v_exp_f32_e32 v100, v96
	s_nop 0
	v_mul_f32_e32 v101, v88, v100
	v_mul_f32_e32 v96, v220, v101
	v_mul_f32_e32 v101, v89, v100
	v_cndmask_b32_e64 v96, 0, v96, s[48:49]
	v_mul_f32_e32 v97, v221, v101
	v_mul_f32_e32 v101, v90, v100
	v_mul_f32_e32 v100, v91, v100
	v_cndmask_b32_e64 v97, 0, v97, s[48:49]
	v_mul_f32_e32 v98, v222, v101
	v_mul_f32_e32 v99, v223, v100
	v_cvt_pk_bf16_f32 v96, v96, v97
	v_cndmask_b32_e64 v98, 0, v98, s[48:49]
	v_cndmask_b32_e64 v99, 0, v99, s[48:49]
	v_cvt_pk_bf16_f32 v97, v98, v99
	ds_write_b64 v149, v[96:97]
	v_readlane_b32 s0, v253, 55
	v_sub_f32_e32 v96, v117, v247
	v_mul_f32_e32 v96, 0x3fb8aa3b, v96
	v_exp_f32_e32 v100, v96
	s_nop 0
	v_mul_f32_e32 v101, v80, v100
	v_mul_f32_e32 v96, v224, v101
	v_mul_f32_e32 v101, v81, v100
	v_cndmask_b32_e64 v96, 0, v96, s[50:51]
	v_mul_f32_e32 v97, v225, v101
	v_mul_f32_e32 v101, v82, v100
	v_mul_f32_e32 v100, v83, v100
	v_cndmask_b32_e64 v97, 0, v97, s[50:51]
	v_mul_f32_e32 v98, v226, v101
	v_mul_f32_e32 v99, v227, v100
	v_cvt_pk_bf16_f32 v96, v96, v97
	v_cndmask_b32_e64 v98, 0, v98, s[50:51]
	v_cndmask_b32_e64 v99, 0, v99, s[50:51]
	v_cvt_pk_bf16_f32 v97, v98, v99
	ds_write_b64 v150, v[96:97]
; #define LAS __attribute__((address_space(3)))
; __device__ __forceinline__ unsigned cvt_pk_bf16(float lo, float hi) { unsigned r; asm volatile("v_cvt_pk_bf16_f32 %0, %1, %2" : "=v"(r) : "v"(lo), "v"(hi)); return r; }
; __device__ __forceinline__ void phase_C1(const Args& a, unsigned char* ws, const int bid, int l, LAS unsigned char* lds, int tid, int wave, int lane) {
;     ...
;               for (int kt = 0; kt < 8; ++kt) { const int k0 = kt * 16 + fq * 4;
;                   const bool kept = dir == 0 ? (kt < qt) : (kt > qt);
;                   const float f1 = __expf(csq - refarr[kt]); const f32x4 f2 = *(const LAS f32x4*)(f2dt + k0);
;                   float m[4];
; #pragma unroll
;                   for (int r = 0; r < 4; ++r) m[r] = kept ? accA[kt][r] * f1 * f2[r] : 0.f;
;                   u32x2 o; o.x = cvt_pk_bf16(m[0], m[1]); o.y = cvt_pk_bf16(m[2], m[3]);
;                   *(LAS u32x2*)(L_M + q * 272 + k0 * 2) = o; }
.Lssd_m_p2:
	s_or_b64 vcc, s[52:53], s[54:55]
	s_or_b64 vcc, vcc, s[16:17]
	s_or_b64 vcc, vcc, s[18:19]
	s_cbranch_vccz .Lssd_m_p3
	v_readlane_b32 s0, v253, 56
	v_sub_f32_e32 v96, v117, v248
	v_mul_f32_e32 v96, 0x3fb8aa3b, v96
	v_exp_f32_e32 v100, v96
	s_nop 0
	v_mul_f32_e32 v101, v92, v100
	v_mul_f32_e32 v96, v228, v101
	v_mul_f32_e32 v101, v93, v100
	v_cndmask_b32_e64 v96, 0, v96, s[52:53]
	v_mul_f32_e32 v97, v229, v101
	v_mul_f32_e32 v101, v94, v100
	v_mul_f32_e32 v100, v95, v100
	v_cndmask_b32_e64 v97, 0, v97, s[52:53]
	v_mul_f32_e32 v98, v230, v101
	v_mul_f32_e32 v99, v231, v100
	v_cvt_pk_bf16_f32 v96, v96, v97
	v_cndmask_b32_e64 v98, 0, v98, s[52:53]
	v_cndmask_b32_e64 v99, 0, v99, s[52:53]
	v_cvt_pk_bf16_f32 v97, v98, v99
	ds_write_b64 v151, v[96:97]
	v_readlane_b32 s0, v253, 57
	v_sub_f32_e32 v96, v117, v249
	v_mul_f32_e32 v96, 0x3fb8aa3b, v96
	v_exp_f32_e32 v100, v96
	s_nop 0
	v_mul_f32_e32 v101, v84, v100
	v_mul_f32_e32 v96, v232, v101
	v_mul_f32_e32 v101, v85, v100
	v_cndmask_b32_e64 v96, 0, v96, s[54:55]
	v_mul_f32_e32 v97, v233, v101
	v_mul_f32_e32 v101, v86, v100
	v_mul_f32_e32 v100, v87, v100
	v_cndmask_b32_e64 v97, 0, v97, s[54:55]
	v_mul_f32_e32 v98, v234, v101
	v_mul_f32_e32 v99, v235, v100
	v_cvt_pk_bf16_f32 v96, v96, v97
	v_cndmask_b32_e64 v98, 0, v98, s[54:55]
	v_cndmask_b32_e64 v99, 0, v99, s[54:55]
	v_cvt_pk_bf16_f32 v97, v98, v99
	ds_write_b64 v152, v[96:97]
.Lssd_m_p3:
	s_or_b64 vcc, s[56:57], s[58:59]
	s_or_b64 vcc, vcc, s[20:21]
	s_or_b64 vcc, vcc, s[22:23]
	s_cbranch_vccz .Lssd_m_p4
	v_readlane_b32 s0, v253, 58
	v_sub_f32_e32 v96, v117, v250
	v_mul_f32_e32 v96, 0x3fb8aa3b, v96
	v_exp_f32_e32 v100, v96
	s_nop 0
	v_mul_f32_e32 v101, v76, v100
	v_mul_f32_e32 v96, v236, v101
	v_mul_f32_e32 v101, v77, v100
	v_cndmask_b32_e64 v96, 0, v96, s[56:57]
	v_mul_f32_e32 v97, v237, v101
	v_mul_f32_e32 v101, v78, v100
	v_mul_f32_e32 v100, v79, v100
	v_cndmask_b32_e64 v97, 0, v97, s[56:57]
	v_mul_f32_e32 v98, v238, v101
	v_mul_f32_e32 v99, v239, v100
	v_cvt_pk_bf16_f32 v96, v96, v97
	v_cndmask_b32_e64 v98, 0, v98, s[56:57]
	v_cndmask_b32_e64 v99, 0, v99, s[56:57]
	v_cvt_pk_bf16_f32 v97, v98, v99
	ds_write_b64 v153, v[96:97]
	v_sub_f32_e32 v96, v117, v251
	v_mul_f32_e32 v96, 0x3fb8aa3b, v96
	v_exp_f32_e32 v100, v96
	s_nop 0
	v_mul_f32_e32 v101, v72, v100
	v_mul_f32_e32 v96, v240, v101
	v_mul_f32_e32 v101, v73, v100
	v_mul_f32_e32 v97, v241, v101
	v_mul_f32_e32 v101, v74, v100
	v_mul_f32_e32 v100, v75, v100
	v_cndmask_b32_e64 v96, 0, v96, s[58:59]
	v_cndmask_b32_e64 v97, 0, v97, s[58:59]
	v_mul_f32_e32 v98, v242, v101
	v_mul_f32_e32 v99, v243, v100
	v_cndmask_b32_e64 v98, 0, v98, s[58:59]
	v_cndmask_b32_e64 v99, 0, v99, s[58:59]
	v_cvt_pk_bf16_f32 v96, v96, v97
	v_cvt_pk_bf16_f32 v97, v98, v99
	ds_write_b64 v154, v[96:97]
.Lssd_m_p4:
	s_and_saveexec_b64 s[0:1], s[60:61]
	s_cbranch_execz .LBB0_123
	v_cndmask_b32_e64 v88, v171, v88, s[12:13]
	v_cndmask_b32_e64 v80, v88, v80, s[14:15]
	v_sub_f32_e32 v88, v117, v180
	v_mul_f32_e32 v88, 0x3fb8aa3b, v88
	v_cndmask_b32_e64 v80, v80, v92, s[16:17]
	v_exp_f32_e32 v88, v88
	v_cndmask_b32_e64 v80, v80, v84, s[18:19]
	v_cndmask_b32_e64 v76, v80, v76, s[20:21]
	v_cndmask_b32_e64 v72, v76, v72, s[22:23]
	v_mul_f32_e32 v72, v72, v88
	v_mul_f32_e32 v172, v184, v72

; #define MFMA16(a, b, c) __builtin_amdgcn_mfma_f32_16x16x32_bf16((a), (b), (c), 0, 0, 0)
; __device__ __forceinline__ void phase_C1(const Args& a, unsigned char* ws, const int bid, int l, LAS unsigned char* lds, int tid, int wave, int lane) {
;     ...
;             {
;                 bf16x8 cqv[2], bq[2][4], hq[2][2];
;     ...
;                 SSD_LDH(0, 0);
; #pragma unroll
;                 for (int h2 = 0; h2 < 8; ++h2) { const int cb = h2 & 1, s_ = h2 >> 1, hf_ = h2 & 1;
;                     if (h2 < 7) SSD_LDH(cb ^ 1, h2 + 1);
;                     __builtin_amdgcn_sched_barrier(0);
; #pragma unroll
;                     for (int k = 0; k < 4; ++k) accA[4 * hf_ + k] = MFMA16(bq[cb][k], cqv[s_ & 1], accA[4 * hf_ + k]);
; #pragma unroll
;                     for (int p = 0; p < 2; ++p) accC[2 * hf_ + p] = MFMA16(hq[cb][p], cqv[s_ & 1], accC[2 * hf_ + p]);
;                     __builtin_amdgcn_sched_barrier(0); }
.Lssd_hb_e:
	s_branch .Lssd_m_section
.Lssd_A_dispatch:
	s_orn2_b64 vcc, s[46:47], s[70:71]
	s_or_b64 vcc, vcc, s[10:11]
	s_cbranch_vccz .Lssd_A_n0_0
	s_or_b64 vcc, s[48:49], s[50:51]
	s_or_b64 vcc, vcc, s[12:13]
	s_or_b64 vcc, vcc, s[14:15]
	s_cbranch_vccz .Lssd_A_1000
	s_or_b64 vcc, s[52:53], s[54:55]
	s_or_b64 vcc, vcc, s[16:17]
	s_or_b64 vcc, vcc, s[18:19]
	s_cbranch_vccz .Lssd_A_1100
	s_or_b64 vcc, s[56:57], s[58:59]
	s_or_b64 vcc, vcc, s[20:21]
	s_or_b64 vcc, vcc, s[22:23]
	s_cbranch_vccz .Lssd_A_1110
	s_branch .Lssd_A_1111
